# diff loop: second fragment buffer moved to the registers freed by LDS-DMA staging (no per-iteration v0/v1 restore), scalar loop control
# baseline (speedup 1.0000x reference)
; DI int opaque_tid() { int t = threadIdx.x; asm volatile("" : "+v"(t)); return t; }
; template <int DV, bool NA> ...
;   const int tid = opaque_tid(), lane = tid & 63;
;   const int h = lane >> 5, r = lane & 31;
;   bf16x8 q[4];
; #pragma unroll
;   for (int ks = 0; ks < 4; ++ks) q[ks] = *(const bf16x8*)(Qp + ks * 16 + h * 8);
; #pragma unroll
;   for (int mv = 0; mv < DV / 32; ++mv)
; #pragma unroll
;     for (int i = 0; i < 16; ++i) o[mv][i] = 0.f;
;   float m_run = -INFINITY, l_run = 0.f;
;   const int lr = tid >> 3, lc = tid & 7;
;   const int wsw = lr * 128 + ((lc ^ ((lr >> 1) & 7)) << 4);
;   u32x4 rk, rv[DV / 64];
;   auto gload = [&](int ti) {
;     const size_t key0 = (size_t)(tile0 + ti) * 64;
;     rk = *(const u32x4*)(Kb + (key0 + lr) * ldk + lc * 8);
; #pragma unroll
;     for (int i = 0; i < DV / 64; ++i) rv[i] = *(const u32x4*)(Vt + (size_t)(lr + 64 * i) * S + key0 + lc * 8);
;   };
;   auto swrite = [&](int st) {
;     char* ks_ = lds + st * ATT_STAGE;
;     *(u32x4*)(ks_ + wsw) = rk;
; #pragma unroll
;     for (int i = 0; i < DV / 64; ++i) *(u32x4*)(ks_ + 8192 + i * 8192 + wsw) = rv[i];
;   };
;   const int pr = (r & 0x13) | ((r & 4) << 1) | ((r & 8) >> 1);
;   const int ksw = (pr >> 1) & 7;
;   const int vsw = (r >> 1) & 7;
;   const int cs_ = NA ? min(max(qc - 8, 0), 48) : 0;
;   __syncthreads();
;   gload(0);
;   swrite(0);
;   if (ntiles > 1) gload(1);
;   __syncthreads();
.LBB0_294:
	v_or_b32_e32 v0, s20, v198
	v_mov_b32_e32 v26, v204
	v_lshlrev_b64 v[2:3], 1, v[0:1]
	v_lshl_add_u64 v[4:5], v[162:163], 0, v[2:3]
	v_bfe_u32 v27, v26, 5, 1
	v_lshl_add_u64 v[2:3], v[160:161], 0, v[2:3]
	v_lshlrev_b32_e32 v0, 4, v27
	v_ashrrev_i32_e32 v14, 3, v26
	v_lshlrev_b32_e32 v28, 4, v26
	v_lshl_add_u64 v[4:5], v[4:5], 0, v[0:1]
	v_ashrrev_i32_e32 v15, 31, v14
	v_mad_i64_i32 v[2:3], s[22:23], v14, s96, v[2:3]
	v_and_b32_e32 v0, 0x70, v28
	v_add_u32_e32 v10, 64, v14
	v_lshl_add_u64 v[16:17], v[2:3], 0, v[0:1]
	v_lshlrev_b64 v[2:3], v176, v[14:15]
	v_ashrrev_i32_e32 v11, 31, v10
	v_lshlrev_b64 v[18:19], 1, v[2:3]
	v_lshlrev_b64 v[10:11], v176, v[10:11]
	v_lshl_add_u64 v[2:3], v[164:165], 0, v[18:19]
	v_lshlrev_b64 v[22:23], 1, v[10:11]
	global_load_dwordx4 v[124:127], v[4:5], off
	global_load_dwordx4 v[120:123], v[4:5], off offset:32
	global_load_dwordx4 v[116:119], v[4:5], off offset:64
	global_load_dwordx4 v[112:115], v[4:5], off offset:96
	s_barrier
	v_lshl_add_u64 v[20:21], v[2:3], 0, v[0:1]
	global_load_dwordx4 v[2:5], v[16:17], off offset:1024
	global_load_dwordx4 v[6:9], v[20:21], off
	v_lshl_add_u64 v[10:11], v[164:165], 0, v[22:23]
	v_lshl_add_u64 v[24:25], v[10:11], 0, v[0:1]
	v_add_co_u32_e32 v16, vcc, s97, v16
	global_load_dwordx4 v[10:13], v[24:25], off
	s_nop 0
	v_addc_co_u32_e32 v17, vcc, 0, v17, vcc
	global_load_dwordx4 v[132:135], v[20:21], off offset:128
	global_load_dwordx4 v[128:131], v[16:17], off offset:1024
	global_load_dwordx4 v[136:139], v[24:25], off offset:128
	v_lshlrev_b32_e32 v15, 1, v26
	v_lshrrev_b32_e32 v20, 1, v26
	v_lshrrev_b32_e32 v16, 5, v26
	v_and_b32_e32 v17, 19, v26
	v_bfe_u32 v21, v26, 1, 3
	v_lshlrev_b32_e32 v24, 7, v26
	v_xor_b32_e32 v26, v28, v26
	v_and_b32_e32 v28, 8, v15
	v_and_b32_e32 v20, 4, v20
	v_bitop3_b32 v16, v16, v21, 1 bitop3:0x6c
	v_or3_b32 v17, v28, v17, v20
	v_lshlrev_b32_e32 v25, 7, v14
	v_and_b32_e32 v178, 0xf80, v24
	v_or_b32_e32 v24, 4, v27
	v_or_b32_e32 v29, 2, v27
	v_or_b32_e32 v30, 6, v27
	v_bitop3_b32 v31, v27, v21, 2 bitop3:0x36
	v_bitop3_b32 v32, v27, v21, 4 bitop3:0x36
	v_bitop3_b32 v21, v27, v21, 6 bitop3:0x36
	v_lshlrev_b32_e32 v195, 4, v16
	v_lshrrev_b32_e32 v16, 1, v17
	v_mad_i64_i32 v[14:15], s[22:23], v14, s96, 0
	v_and_or_b32 v203, v26, s66, v25
	v_lshlrev_b32_e32 v179, 4, v21
	v_lshlrev_b32_e32 v228, 7, v17
	v_bitop3_b32 v20, v16, v27, 7 bitop3:0x6c
	v_bitop3_b32 v21, v16, v29, 7 bitop3:0x6c
	v_bitop3_b32 v24, v16, v24, 7 bitop3:0x6c
	v_bitop3_b32 v25, v16, v30, 7 bitop3:0x6c
	v_lshl_add_u64 v[16:17], v[0:1], 0, v[18:19]
	v_or_b32_e32 v14, v14, v0
	v_lshl_add_u64 v[170:171], v[166:167], 0, v[16:17]
	v_lshl_add_u64 v[16:17], v[0:1], 0, v[22:23]
	v_add_u32_e32 v0, s20, v198
	s_waitcnt vmcnt(18)
	v_lshlrev_b32_e32 v183, 4, v31
	v_lshlrev_b32_e32 v181, 4, v32
	v_lshlrev_b32_e32 v229, 4, v20
	v_lshlrev_b32_e32 v202, 4, v21
	v_lshlrev_b32_e32 v201, 4, v24
	v_lshlrev_b32_e32 v200, 4, v25
	v_lshl_add_u64 v[172:173], v[166:167], 0, v[16:17]
	v_mov_b32_e32 v180, 0
	v_mov_b32_e32 v182, 0xff800000
	s_mov_b64 s[20:21], 0
	s_mov_b32 s31, 0
	s_waitcnt vmcnt(5)
	ds_write_b128 v203, v[2:5]
	s_waitcnt vmcnt(4)
	ds_write_b128 v203, v[6:9] offset:8192
	s_waitcnt vmcnt(3)
	ds_write_b128 v203, v[10:13] offset:16384
	v_lshl_add_u64 v[2:3], v[0:1], 1, v[14:15]
	v_mov_b32_e32 v14, v1
	v_mov_b32_e32 v15, v1
	v_lshl_add_u64 v[174:175], v[168:169], 0, v[2:3]
	v_mov_b32_e32 v0, v1
	v_mov_b32_e32 v2, v1
	v_mov_b32_e32 v3, v1
	v_mov_b32_e32 v4, v1
	v_mov_b32_e32 v5, v1
	v_mov_b32_e32 v6, v1
	v_mov_b32_e32 v7, v1
	v_mov_b32_e32 v8, v1
	v_mov_b32_e32 v9, v1
	v_mov_b32_e32 v10, v1
	v_mov_b32_e32 v11, v1
	v_mov_b32_e32 v12, v1
	v_mov_b32_e32 v13, v1
	v_mov_b64_e32 v[30:31], v[14:15]
	v_mov_b64_e32 v[46:47], v[14:15]
	v_mov_b64_e32 v[62:63], v[14:15]
	v_mov_b64_e32 v[78:79], v[14:15]
	v_mov_b64_e32 v[28:29], v[12:13]
	v_mov_b64_e32 v[26:27], v[10:11]
	v_mov_b64_e32 v[24:25], v[8:9]
	v_mov_b64_e32 v[22:23], v[6:7]
	v_mov_b64_e32 v[20:21], v[4:5]
	v_mov_b64_e32 v[18:19], v[2:3]
	v_mov_b64_e32 v[16:17], v[0:1]
	v_mov_b64_e32 v[44:45], v[12:13]
	v_mov_b64_e32 v[42:43], v[10:11]
	v_mov_b64_e32 v[40:41], v[8:9]
	v_mov_b64_e32 v[38:39], v[6:7]
	v_mov_b64_e32 v[36:37], v[4:5]
	v_mov_b64_e32 v[34:35], v[2:3]
	v_mov_b64_e32 v[32:33], v[0:1]
	v_mov_b64_e32 v[60:61], v[12:13]
	v_mov_b64_e32 v[58:59], v[10:11]
	v_mov_b64_e32 v[56:57], v[8:9]
	v_mov_b64_e32 v[54:55], v[6:7]
	v_mov_b64_e32 v[52:53], v[4:5]
	v_mov_b64_e32 v[50:51], v[2:3]
	v_mov_b64_e32 v[48:49], v[0:1]
	v_mov_b64_e32 v[76:77], v[12:13]
	v_mov_b64_e32 v[74:75], v[10:11]
	v_mov_b64_e32 v[72:73], v[8:9]
	v_mov_b64_e32 v[70:71], v[6:7]
	v_mov_b64_e32 v[68:69], v[4:5]
	v_mov_b64_e32 v[66:67], v[2:3]
	v_mov_b64_e32 v[64:65], v[0:1]
	v_mov_b32_e32 v182, 0
	s_mov_b32 s100, 0xff800000
	v_mov_b32_e32 v234, 0
	v_mov_b32_e32 v235, 0
	v_mov_b32_e32 v236, 0
	v_mov_b32_e32 v237, 0
	v_mov_b32_e32 v238, 0
	v_mov_b32_e32 v239, 0
	v_mov_b32_e32 v240, 0
	v_mov_b32_e32 v241, 0
	v_mov_b32_e32 v242, 0
	v_mov_b32_e32 v243, 0
	v_mov_b32_e32 v244, 0
	v_mov_b32_e32 v245, 0
	v_mov_b32_e32 v246, 0
	v_mov_b32_e32 v247, 0
	v_mov_b32_e32 v248, 0
	v_mov_b32_e32 v249, 0
	v_add_u32_e32 v159, 0x6000, v203
	s_waitcnt vmcnt(1)
	ds_write_b128 v159, v[128:131]
	ds_write_b128 v159, v[132:135] offset:8192
	s_waitcnt vmcnt(0)
	ds_write_b128 v159, v[136:139] offset:16384
	v_and_b32_e32 v231, 7, v204
	v_bfe_u32 v232, v204, 4, 3
	v_xor_b32_e32 v232, v232, v231
	v_sub_u32_e32 v232, v232, v231
	v_lshlrev_b32_e32 v232, 4, v232
	v_ashrrev_i32_e32 v233, 31, v232
	v_lshl_add_u64 v[174:175], v[174:175], 0, v[232:233]
	v_lshl_add_u64 v[170:171], v[170:171], 0, v[232:233]
	v_lshl_add_u64 v[172:173], v[172:173], 0, v[232:233]
	v_readfirstlane_b32 s23, v185
	v_readfirstlane_b32 s20, v177
	s_mov_b32 s21, 0
	v_readfirstlane_b32 s101, v204
	s_mov_b32 s30, 0xc000
	s_mov_b32 s22, 0
	s_lshr_b32 s101, s101, 6
	s_lshl_b32 s101, s101, 10
	s_waitcnt lgkmcnt(0)
	s_barrier
	s_branch .LBB0_296

; #define MFMA(a, b, c) __builtin_amdgcn_mfma_f32_32x32x16_bf16((a), (b), (c), 0, 0, 0)
; DI float fexp2(float x) { return __builtin_amdgcn_exp2f(x); }
; template <int DV, bool NA> ...
;     ...
;       {
;         bf16x8 ka[4], kb_[4];
; #pragma unroll
;         for (int ks = 0; ks < 4; ++ks) {
;           const int co = ((2 * ks + h) ^ ksw) << 4;
;           ka[ks] = *(const bf16x8*)(st + pr * 128 + co);
;           kb_[ks] = *(const bf16x8*)(st + (32 + pr) * 128 + co);
;         }
;         asm volatile("" ::: "memory");
; #pragma unroll
;         for (int ks = 0; ks < 4; ++ks) {
;           s0 = MFMA(ka[ks], q[ks], s0);
;           s1 = MFMA(kb_[ks], q[ks], s1);
;         }
;       }
;       bf16x8 vf0[2][DV / 32];
; #pragma unroll
;       for (int c2 = 0; c2 < 2; ++c2) {
;         const int co = ((2 * c2 + h) ^ vsw) << 4;
; #pragma unroll
;         for (int mv = 0; mv < DV / 32; ++mv) vf0[c2][mv] = *(const bf16x8*)(st + 8192 + (mv * 32 + r) * 128 + co);
;       }
;       asm volatile("" ::: "memory");
;       float t[32];
; #pragma unroll
;       for (int i = 0; i < 16; ++i) { t[i] = s0[i]; t[16 + i] = s1[i]; }
;     ...
;       float ls = 0.f;
; #pragma unroll
;       for (int e = 0; e < 32; ++e) { t[e] = fexp2(t[e] - m_run); ls += t[e]; }
;       l_run += ls;
;       bf16x8 pf[2][2];
; #pragma unroll
;       for (int kb = 0; kb < 2; ++kb)
; #pragma unroll
;         for (int c2 = 0; c2 < 2; ++c2) {
;           const int e0 = kb * 16 + c2 * 8;
;           u32x4 pw = {pk_bf16(t[e0], t[e0 + 1]), pk_bf16(t[e0 + 2], t[e0 + 3]), pk_bf16(t[e0 + 4], t[e0 + 5]), pk_bf16(t[e0 + 6], t[e0 + 7])};
;           pf[kb][c2] = __builtin_bit_cast(bf16x8, pw);
;         }
;       bf16x8 vf1[2][DV / 32];
; #pragma unroll
;       for (int c2 = 0; c2 < 2; ++c2) {
;         const int co = ((4 + 2 * c2 + h) ^ vsw) << 4;
; #pragma unroll
;         for (int mv = 0; mv < DV / 32; ++mv) vf1[c2][mv] = *(const bf16x8*)(st + 8192 + (mv * 32 + r) * 128 + co);
;       }
;       asm volatile("" ::: "memory");
; #pragma unroll
;       for (int c2 = 0; c2 < 2; ++c2)
; #pragma unroll
;         for (int mv = 0; mv < DV / 32; ++mv) o[mv] = MFMA(vf0[c2][mv], pf[0][c2], o[mv]);
; #pragma unroll
;       for (int c2 = 0; c2 < 2; ++c2)
; #pragma unroll
;         for (int mv = 0; mv < DV / 32; ++mv) o[mv] = MFMA(vf1[c2][mv], pf[1][c2], o[mv]);
;     }
;     __syncthreads();
.Ldf_dmadone:
	v_add_u32_e32 v158, s22, v228
	v_add_u32_e32 v159, v158, v229
	ds_read_b128 v[128:131], v159
	ds_read_b128 v[132:135], v159 offset:4096
	v_add_u32_e32 v159, v158, v202
	ds_read_b128 v[136:139], v159
	ds_read_b128 v[12:15], v159 offset:4096
	v_add3_u32 v210, s22, v195, v178
	s_waitcnt lgkmcnt(2)
	v_mfma_f32_32x32x16_bf16 v[96:111], v[128:131], v[124:127], v[234:249]
	v_mfma_f32_32x32x16_bf16 v[80:95], v[132:135], v[124:127], v[234:249]
	v_add_u32_e32 v159, v158, v201
	ds_read_b128 v[128:131], v159
	ds_read_b128 v[132:135], v159 offset:4096
	s_waitcnt lgkmcnt(2)
	v_mfma_f32_32x32x16_bf16 v[96:111], v[136:139], v[120:123], v[96:111]
	v_mfma_f32_32x32x16_bf16 v[80:95], v[12:15], v[120:123], v[80:95]
	v_add_u32_e32 v159, v158, v200
	ds_read_b128 v[136:139], v159
	ds_read_b128 v[12:15], v159 offset:4096
	ds_read_b128 v[140:143], v210 offset:8192
	ds_read_b128 v[144:147], v210 offset:12288
	ds_read_b128 v[148:151], v210 offset:16384
	ds_read_b128 v[152:155], v210 offset:20480
	v_add3_u32 v230, s22, v183, v178
	s_waitcnt lgkmcnt(6)
	v_mfma_f32_32x32x16_bf16 v[96:111], v[128:131], v[116:119], v[96:111]
	v_mfma_f32_32x32x16_bf16 v[80:95], v[132:135], v[116:119], v[80:95]
	s_waitcnt lgkmcnt(4)
	v_mfma_f32_32x32x16_bf16 v[96:111], v[136:139], v[112:115], v[96:111]
	v_mfma_f32_32x32x16_bf16 v[80:95], v[12:15], v[112:115], v[80:95]
	ds_read_b128 v[128:131], v230 offset:8192
	ds_read_b128 v[132:135], v230 offset:12288
	ds_read_b128 v[136:139], v230 offset:16384
	ds_read_b128 v[12:15], v230 offset:20480
	v_add3_u32 v210, s22, v181, v178
	v_add3_u32 v230, s22, v179, v178
.Ldf_exps:
	s_nop 4
	v_exp_f32_e32 v96, v96
	v_exp_f32_e32 v97, v97
	v_exp_f32_e32 v98, v98
	v_exp_f32_e32 v99, v99
	v_exp_f32_e32 v100, v100
	v_exp_f32_e32 v101, v101
	v_exp_f32_e32 v102, v102
	v_exp_f32_e32 v103, v103
	v_exp_f32_e32 v104, v104
	v_exp_f32_e32 v105, v105
	v_add_f32_e32 v156, v96, v98
	v_add_f32_e32 v157, v97, v99
	v_exp_f32_e32 v106, v106
	v_exp_f32_e32 v107, v107
	v_add_f32_e32 v156, v156, v100
	v_add_f32_e32 v157, v157, v101
	v_exp_f32_e32 v108, v108
	v_exp_f32_e32 v109, v109
	v_add_f32_e32 v156, v156, v102
	v_add_f32_e32 v157, v157, v103
	v_exp_f32_e32 v110, v110
	v_exp_f32_e32 v111, v111
	v_add_f32_e32 v156, v156, v104
	v_add_f32_e32 v157, v157, v105
	v_exp_f32_e32 v80, v80
	v_exp_f32_e32 v81, v81
	v_add_f32_e32 v156, v156, v106
	v_add_f32_e32 v157, v157, v107
	v_exp_f32_e32 v82, v82
	v_exp_f32_e32 v83, v83
	v_add_f32_e32 v156, v156, v108
	v_add_f32_e32 v157, v157, v109
	v_exp_f32_e32 v84, v84
	v_exp_f32_e32 v85, v85
	v_add_f32_e32 v156, v156, v110
	v_add_f32_e32 v157, v157, v111
	v_exp_f32_e32 v86, v86
	v_exp_f32_e32 v87, v87
	v_add_f32_e32 v156, v156, v80
	v_add_f32_e32 v157, v157, v81
	v_exp_f32_e32 v88, v88
	v_exp_f32_e32 v89, v89
	v_add_f32_e32 v156, v156, v82
	v_add_f32_e32 v157, v157, v83
	v_exp_f32_e32 v90, v90
	v_exp_f32_e32 v91, v91
	v_add_f32_e32 v156, v156, v84
	v_add_f32_e32 v157, v157, v85
	v_exp_f32_e32 v92, v92
	v_exp_f32_e32 v93, v93
	v_add_f32_e32 v156, v156, v86
	v_add_f32_e32 v157, v157, v87
	v_exp_f32_e32 v94, v94
	v_exp_f32_e32 v95, v95
	v_add_f32_e32 v156, v156, v88
	v_add_f32_e32 v157, v157, v89
	v_add_f32_e32 v156, v156, v90
	v_add_f32_e32 v157, v157, v91
	v_add_f32_e32 v156, v156, v92
	v_add_f32_e32 v157, v157, v93
	v_add_f32_e32 v156, v156, v94
	v_add_f32_e32 v157, v157, v95
	v_add_f32_e32 v156, v156, v157
	v_cmp_lt_f32_e32 vcc, s100, v156
	s_cbranch_vccnz .Ldf_fix
	v_add_f32_e32 v180, v180, v156
	v_cvt_pk_bf16_f32 v96, v96, v97
	v_cvt_pk_bf16_f32 v97, v98, v99
	v_cvt_pk_bf16_f32 v98, v100, v101
	v_cvt_pk_bf16_f32 v99, v102, v103
	s_waitcnt lgkmcnt(4)
	s_nop 0
	v_mfma_f32_32x32x16_bf16 v[64:79], v[140:143], v[96:99], v[64:79]
	v_cvt_pk_bf16_f32 v104, v104, v105
	v_mfma_f32_32x32x16_bf16 v[48:63], v[144:147], v[96:99], v[48:63]
	v_cvt_pk_bf16_f32 v105, v106, v107
	v_mfma_f32_32x32x16_bf16 v[32:47], v[148:151], v[96:99], v[32:47]
	v_cvt_pk_bf16_f32 v106, v108, v109
	v_mfma_f32_32x32x16_bf16 v[16:31], v[152:155], v[96:99], v[16:31]
	v_cvt_pk_bf16_f32 v107, v110, v111
	ds_read_b128 v[140:143], v210 offset:8192
	ds_read_b128 v[144:147], v210 offset:12288
	ds_read_b128 v[148:151], v210 offset:16384
	ds_read_b128 v[152:155], v210 offset:20480
	s_waitcnt lgkmcnt(4)
	v_mfma_f32_32x32x16_bf16 v[64:79], v[128:131], v[104:107], v[64:79]
	v_cvt_pk_bf16_f32 v80, v80, v81
	v_mfma_f32_32x32x16_bf16 v[48:63], v[132:135], v[104:107], v[48:63]
	v_cvt_pk_bf16_f32 v81, v82, v83
	v_mfma_f32_32x32x16_bf16 v[32:47], v[136:139], v[104:107], v[32:47]
	v_cvt_pk_bf16_f32 v82, v84, v85
	v_mfma_f32_32x32x16_bf16 v[16:31], v[12:15], v[104:107], v[16:31]
	v_cvt_pk_bf16_f32 v83, v86, v87
	ds_read_b128 v[128:131], v230 offset:8192
	ds_read_b128 v[132:135], v230 offset:12288
	ds_read_b128 v[136:139], v230 offset:16384
	ds_read_b128 v[12:15], v230 offset:20480
	s_waitcnt lgkmcnt(4)
	v_mfma_f32_32x32x16_bf16 v[64:79], v[140:143], v[80:83], v[64:79]
	v_cvt_pk_bf16_f32 v88, v88, v89
	v_mfma_f32_32x32x16_bf16 v[48:63], v[144:147], v[80:83], v[48:63]
	v_cvt_pk_bf16_f32 v89, v90, v91
	v_mfma_f32_32x32x16_bf16 v[32:47], v[148:151], v[80:83], v[32:47]
	v_cvt_pk_bf16_f32 v90, v92, v93
	v_mfma_f32_32x32x16_bf16 v[16:31], v[152:155], v[80:83], v[16:31]
	v_cvt_pk_bf16_f32 v91, v94, v95
	s_waitcnt lgkmcnt(0)
	s_nop 0
	v_mfma_f32_32x32x16_bf16 v[64:79], v[128:131], v[88:91], v[64:79]
	v_mfma_f32_32x32x16_bf16 v[48:63], v[132:135], v[88:91], v[48:63]
	v_mfma_f32_32x32x16_bf16 v[32:47], v[136:139], v[88:91], v[32:47]
	v_mfma_f32_32x32x16_bf16 v[16:31], v[12:15], v[88:91], v[16:31]
	s_add_u32 vcc_lo, s22, s30
	s_mov_b32 s30, s22
	s_sub_u32 s22, 0x12000, vcc_lo
	s_mov_b32 s31, s29
	s_waitcnt vmcnt(3)
	s_waitcnt lgkmcnt(0)
	s_barrier
	s_cmp_lg_u32 s31, s20
	s_cbranch_scc1 .LBB0_296
	v_mov_b32_e32 v0, s22
	v_readfirstlane_b32 s101, v204
	s_nop 0
	s_lshr_b32 s101, s101, 8
	s_branch .LBB0_300
; #define MFMA(a, b, c) __builtin_amdgcn_mfma_f32_32x32x16_bf16((a), (b), (c), 0, 0, 0)
; DI float fexp2(float x) { return __builtin_amdgcn_exp2f(x); }
; template <int DV, bool NA> ...
;     ...
;       {
;         bf16x8 ka[4], kb_[4];
; #pragma unroll
;         for (int ks = 0; ks < 4; ++ks) {
;           const int co = ((2 * ks + h) ^ ksw) << 4;
;           ka[ks] = *(const bf16x8*)(st + pr * 128 + co);
;           kb_[ks] = *(const bf16x8*)(st + (32 + pr) * 128 + co);
;         }
;         asm volatile("" ::: "memory");
; #pragma unroll
;         for (int ks = 0; ks < 4; ++ks) {
;           s0 = MFMA(ka[ks], q[ks], s0);
;           s1 = MFMA(kb_[ks], q[ks], s1);
;         }
;     ...
;       float mx = t[0];
; #pragma unroll
;       for (int e = 1; e < 32; ++e) mx = fmaxf(mx, t[e]);
;       mx = fmaxf(mx, __shfl_xor(mx, 32));
;       if (__builtin_amdgcn_ballot_w64(mx > m_run + 8.f) != 0ull) {
;         const float m_new = fmaxf(m_run, mx);
;         const float alpha = fexp2(m_run - m_new);
;         l_run *= alpha;
;         m_run = m_new;
; #pragma unroll
;         for (int mv = 0; mv < DV / 32; ++mv)
; #pragma unroll
;           for (int i = 0; i < 16; ++i) o[mv][i] *= alpha;
;       }
;       float ls = 0.f;
; #pragma unroll
;       for (int e = 0; e < 32; ++e) { t[e] = fexp2(t[e] - m_run); ls += t[e]; }
;       l_run += ls;
.Ldf_fix:
	s_waitcnt lgkmcnt(0)
	v_add_u32_e32 v158, s22, v228
	v_add_u32_e32 v159, v158, v229
	ds_read_b128 v[128:131], v159
	ds_read_b128 v[132:135], v159 offset:4096
	v_add_u32_e32 v159, v158, v202
	ds_read_b128 v[136:139], v159
	ds_read_b128 v[12:15], v159 offset:4096
	s_waitcnt lgkmcnt(2)
	v_mfma_f32_32x32x16_bf16 v[96:111], v[128:131], v[124:127], v[234:249]
	v_mfma_f32_32x32x16_bf16 v[80:95], v[132:135], v[124:127], v[234:249]
	v_add_u32_e32 v159, v158, v201
	ds_read_b128 v[128:131], v159
	ds_read_b128 v[132:135], v159 offset:4096
	s_waitcnt lgkmcnt(2)
	v_mfma_f32_32x32x16_bf16 v[96:111], v[136:139], v[120:123], v[96:111]
	v_mfma_f32_32x32x16_bf16 v[80:95], v[12:15], v[120:123], v[80:95]
	v_add_u32_e32 v159, v158, v200
	ds_read_b128 v[136:139], v159
	ds_read_b128 v[12:15], v159 offset:4096
	v_add3_u32 v230, s22, v183, v178
	s_waitcnt lgkmcnt(2)
	v_mfma_f32_32x32x16_bf16 v[96:111], v[128:131], v[116:119], v[96:111]
	v_mfma_f32_32x32x16_bf16 v[80:95], v[132:135], v[116:119], v[80:95]
	s_waitcnt lgkmcnt(0)
	v_mfma_f32_32x32x16_bf16 v[96:111], v[136:139], v[112:115], v[96:111]
	v_mfma_f32_32x32x16_bf16 v[80:95], v[12:15], v[112:115], v[80:95]
	ds_read_b128 v[128:131], v230 offset:8192
	ds_read_b128 v[132:135], v230 offset:12288
	ds_read_b128 v[136:139], v230 offset:16384
	ds_read_b128 v[12:15], v230 offset:20480
	s_nop 6
	v_max3_f32 v156, v96, v97, v98
	v_max3_f32 v157, v105, v106, v107
	v_max3_f32 v158, v80, v81, v82
	v_max3_f32 v159, v89, v90, v91
	v_max3_f32 v156, v156, v99, v100
	v_max3_f32 v157, v157, v108, v109
	v_max3_f32 v158, v158, v83, v84
	v_max3_f32 v159, v159, v92, v93
	v_max3_f32 v156, v156, v101, v102
	v_max3_f32 v157, v157, v110, v111
	v_max3_f32 v158, v158, v85, v86
	v_max3_f32 v159, v159, v94, v95
	v_max3_f32 v156, v156, v103, v104
	v_max3_f32 v158, v158, v87, v88
	v_max3_f32 v156, v156, v157, v158
	v_max_f32_e32 v156, v156, v159
	v_mov_b32_e32 v157, v156
	v_mov_b32_e32 v158, s100
	s_nop 0
	v_permlane32_swap_b32_e32 v156, v157
	v_max_f32_e32 v156, v156, v157
	v_max_f32_e32 v158, 0xff800000, v158
	v_cmp_class_f32_e64 vcc, v158, 4
	v_max_f32_e32 v157, 0, v156
	s_nop 1
	v_cndmask_b32_e32 v157, v157, v156, vcc
	s_mov_b32 s100, 0x5d800000
	v_add_f32_e32 v182, v182, v157
	v_min_f32_e64 v158, -v157, 0
	v_exp_f32_e32 v158, v158
	v_sub_f32_e32 v234, v234, v157
	v_sub_f32_e32 v235, v235, v157
	v_sub_f32_e32 v236, v236, v157
	v_sub_f32_e32 v237, v237, v157
	v_sub_f32_e32 v238, v238, v157
	v_sub_f32_e32 v239, v239, v157
	v_sub_f32_e32 v240, v240, v157
	v_sub_f32_e32 v241, v241, v157
	v_sub_f32_e32 v242, v242, v157
	v_sub_f32_e32 v243, v243, v157
	v_sub_f32_e32 v244, v244, v157
	v_sub_f32_e32 v245, v245, v157
	v_sub_f32_e32 v246, v246, v157
	v_sub_f32_e32 v247, v247, v157
	v_sub_f32_e32 v248, v248, v157
	v_sub_f32_e32 v249, v249, v157
	v_sub_f32_e32 v80, v80, v157
	v_sub_f32_e32 v81, v81, v157
	v_sub_f32_e32 v82, v82, v157
	v_sub_f32_e32 v83, v83, v157
	v_sub_f32_e32 v84, v84, v157
	v_sub_f32_e32 v85, v85, v157
	v_sub_f32_e32 v86, v86, v157
	v_sub_f32_e32 v87, v87, v157
	v_sub_f32_e32 v88, v88, v157
	v_sub_f32_e32 v89, v89, v157
	v_sub_f32_e32 v90, v90, v157
	v_sub_f32_e32 v91, v91, v157
	v_sub_f32_e32 v92, v92, v157
	v_sub_f32_e32 v93, v93, v157
	v_sub_f32_e32 v94, v94, v157
	v_sub_f32_e32 v95, v95, v157
	v_sub_f32_e32 v96, v96, v157
	v_sub_f32_e32 v97, v97, v157
	v_sub_f32_e32 v98, v98, v157
	v_sub_f32_e32 v99, v99, v157
	v_sub_f32_e32 v100, v100, v157
	v_sub_f32_e32 v101, v101, v157
	v_sub_f32_e32 v102, v102, v157
	v_sub_f32_e32 v103, v103, v157
	v_sub_f32_e32 v104, v104, v157
	v_sub_f32_e32 v105, v105, v157
	v_sub_f32_e32 v106, v106, v157
	v_sub_f32_e32 v107, v107, v157
	v_sub_f32_e32 v108, v108, v157
	v_sub_f32_e32 v109, v109, v157
	v_sub_f32_e32 v110, v110, v157
	v_sub_f32_e32 v111, v111, v157
	v_pk_mul_f32 v[16:17], v[16:17], v[158:159] op_sel_hi:[1,0]
	v_pk_mul_f32 v[18:19], v[18:19], v[158:159] op_sel_hi:[1,0]
	v_pk_mul_f32 v[20:21], v[20:21], v[158:159] op_sel_hi:[1,0]
	v_pk_mul_f32 v[22:23], v[22:23], v[158:159] op_sel_hi:[1,0]
	v_pk_mul_f32 v[24:25], v[24:25], v[158:159] op_sel_hi:[1,0]
	v_pk_mul_f32 v[26:27], v[26:27], v[158:159] op_sel_hi:[1,0]
	v_pk_mul_f32 v[28:29], v[28:29], v[158:159] op_sel_hi:[1,0]
	v_pk_mul_f32 v[30:31], v[30:31], v[158:159] op_sel_hi:[1,0]
	v_pk_mul_f32 v[32:33], v[32:33], v[158:159] op_sel_hi:[1,0]
	v_pk_mul_f32 v[34:35], v[34:35], v[158:159] op_sel_hi:[1,0]
	v_pk_mul_f32 v[36:37], v[36:37], v[158:159] op_sel_hi:[1,0]
	v_pk_mul_f32 v[38:39], v[38:39], v[158:159] op_sel_hi:[1,0]
	v_pk_mul_f32 v[40:41], v[40:41], v[158:159] op_sel_hi:[1,0]
	v_pk_mul_f32 v[42:43], v[42:43], v[158:159] op_sel_hi:[1,0]
	v_pk_mul_f32 v[44:45], v[44:45], v[158:159] op_sel_hi:[1,0]
	v_pk_mul_f32 v[46:47], v[46:47], v[158:159] op_sel_hi:[1,0]
	v_pk_mul_f32 v[48:49], v[48:49], v[158:159] op_sel_hi:[1,0]
	v_pk_mul_f32 v[50:51], v[50:51], v[158:159] op_sel_hi:[1,0]
	v_pk_mul_f32 v[52:53], v[52:53], v[158:159] op_sel_hi:[1,0]
	v_pk_mul_f32 v[54:55], v[54:55], v[158:159] op_sel_hi:[1,0]
	v_pk_mul_f32 v[56:57], v[56:57], v[158:159] op_sel_hi:[1,0]
	v_pk_mul_f32 v[58:59], v[58:59], v[158:159] op_sel_hi:[1,0]
	v_pk_mul_f32 v[60:61], v[60:61], v[158:159] op_sel_hi:[1,0]
	v_pk_mul_f32 v[62:63], v[62:63], v[158:159] op_sel_hi:[1,0]
	v_pk_mul_f32 v[64:65], v[64:65], v[158:159] op_sel_hi:[1,0]
	v_pk_mul_f32 v[66:67], v[66:67], v[158:159] op_sel_hi:[1,0]
	v_pk_mul_f32 v[68:69], v[68:69], v[158:159] op_sel_hi:[1,0]
	v_pk_mul_f32 v[70:71], v[70:71], v[158:159] op_sel_hi:[1,0]
	v_pk_mul_f32 v[72:73], v[72:73], v[158:159] op_sel_hi:[1,0]
	v_pk_mul_f32 v[74:75], v[74:75], v[158:159] op_sel_hi:[1,0]
	v_pk_mul_f32 v[76:77], v[76:77], v[158:159] op_sel_hi:[1,0]
	v_pk_mul_f32 v[78:79], v[78:79], v[158:159] op_sel_hi:[1,0]
	v_mul_f32_e32 v180, v180, v158
	v_add3_u32 v230, s22, v179, v178
	s_branch .Ldf_exps
